# baseline (speedup 1.0000x reference)
.LBB0_181:
	v_mov_b32_e32 v97, v208
	s_and_b32 s2, s99, 7
	v_ashrrev_i32_e32 v0, 31, v97
	v_lshrrev_b32_e32 v0, 26, v0
	v_add_u32_e32 v0, v97, v0
	v_ashrrev_i32_e32 v8, 6, v0
	v_bfe_i32 v0, v97, 27, 1
	v_lshlrev_b32_e32 v12, 4, v97
	v_lshrrev_b32_e32 v0, 22, v0
	v_add_u32_e32 v0, v12, v0
	v_and_b32_e32 v0, 0xfffffc00, v0
	v_sub_u32_e32 v0, v12, v0
	v_lshrrev_b32_e32 v1, 4, v0
	v_bitop3_b32 v0, v1, v0, 32 bitop3:0x6c
	v_ashrrev_i32_e32 v2, 31, v0
	v_lshrrev_b32_e32 v2, 26, v2
	v_add_u32_e32 v2, v0, v2
	v_ashrrev_i32_e32 v9, 6, v2
	v_and_b32_e32 v2, 0xc0, v2
	v_sub_u32_e32 v0, v0, v2
	v_lshlrev_b32_e32 v1, 3, v8
	v_lshlrev_b32_e32 v3, 5, v8
	v_ashrrev_i16_sdwa v0, v209, sext(v0) dst_sel:DWORD dst_unused:UNUSED_PAD src0_sel:DWORD src1_sel:BYTE_0
	v_and_b32_e32 v1, 0xffff0, v1
	v_and_b32_e32 v3, 32, v3
	v_bfe_i32 v10, v0, 0, 16
	v_add_u32_e32 v0, v3, v10
	v_add_lshl_u32 v1, v9, v1, 12
	s_ashr_i32 s4, s99, 3
	s_mulk_i32 s2, 0xd0
	v_lshl_add_u32 v174, v0, 1, v1
	v_add_u32_e32 v0, 0x2000, v12
	s_add_i32 s2, s2, s4
	v_ashrrev_i32_e32 v1, 31, v0
	s_mul_hi_i32 s4, s2, 0x4ec4ec4f
	v_lshrrev_b32_e32 v1, 22, v1
	s_lshr_b32 s5, s4, 31
	s_ashr_i32 s4, s4, 6
	v_add_u32_e32 v1, v0, v1
	s_add_i32 s4, s4, s5
	v_ashrrev_i32_e32 v11, 10, v1
	s_mul_i32 s5, s4, 0xd0
	v_mul_i32_i24_e32 v1, 0x400, v11
	s_sub_i32 s2, s2, s5
	v_sub_u32_e32 v0, v0, v1
	s_lshl_b32 s48, s2, 8
	v_lshrrev_b32_e32 v1, 4, v0
	s_lshl_b32 s4, s4, 11
	s_and_b32 s5, s48, 0x700
	v_bitop3_b32 v0, v1, v0, 32 bitop3:0x6c
	s_or_b32 s4, s5, s4
	s_lshr_b32 s5, s4, 1
	s_and_b32 s5, s5, 0xfffffc00
	s_bfe_u32 s6, s4, 0x1000a
	s_lshl_b32 s6, s6, 13
	s_and_b32 s4, s4, 0x300
	s_or_b32 s4, s4, s5
	s_or_b32 s4, s4, s6
	v_ashrrev_i32_e32 v2, 31, v0
	s_ashr_i32 s49, s2, 3
	v_lshrrev_b32_e32 v2, 26, v2
	s_ashr_i32 s5, s4, 31
	s_lshl_b32 s6, s49, 8
	v_add_u32_e32 v2, v0, v2
	s_lshl_b64 s[8:9], s[4:5], 12
	v_ashrrev_i32_e32 v13, 6, v2
	v_and_b32_e32 v2, 0xc0, v2
	s_add_u32 s8, s33, s8
	v_sub_u32_e32 v0, v0, v2
	s_addc_u32 s9, s58, s9
	s_ashr_i32 s7, s6, 31
	v_lshlrev_b32_e32 v1, 3, v11
	v_lshlrev_b32_e32 v3, 5, v11
	v_ashrrev_i16_sdwa v0, v209, sext(v0) dst_sel:DWORD dst_unused:UNUSED_PAD src0_sel:DWORD src1_sel:BYTE_0
	s_lshl_b64 s[10:11], s[6:7], 12
	v_add_u32_e32 v144, s71, v12
	v_and_b32_e32 v1, 0xffff0, v1
	v_and_b32_e32 v3, 32, v3
	v_bfe_i32 v14, v0, 0, 16
	s_add_u32 s10, s59, s10
	v_readfirstlane_b32 s2, v144
	v_add_u32_e32 v146, 0x2000, v144
	v_add_u32_e32 v0, v3, v14
	v_add_lshl_u32 v1, v13, v1, 12
	s_addc_u32 s11, s76, s11
	s_mov_b32 m0, s2
	v_readfirstlane_b32 s2, v146
	v_add_u32_e32 v147, 0, v12
	v_lshl_add_u32 v130, v0, 1, v1
	global_load_lds_dwordx4 v174, s[10:11]
	s_mov_b32 m0, s2
	v_readfirstlane_b32 s2, v147
	v_add_u32_e32 v148, 0x2000, v147
	global_load_lds_dwordx4 v130, s[10:11]
	s_mov_b32 m0, s2
	v_readfirstlane_b32 s2, v148
	global_load_lds_dwordx4 v174, s[8:9]
	s_mov_b32 m0, s2
	v_readlane_b32 s2, v254, 20
	s_add_u32 s12, s10, 0x80000
	global_load_lds_dwordx4 v130, s[8:9]
	v_add_u32_e32 v149, s2, v12
	v_add_u32_e32 v150, 0x2000, v149
	v_readfirstlane_b32 s2, v149
	s_addc_u32 s13, s11, 0
	s_mov_b32 m0, s2
	v_readfirstlane_b32 s2, v150
	global_load_lds_dwordx4 v174, s[12:13]
	s_mov_b32 m0, s2
	v_add_u32_e32 v152, 0x4000, v147
	global_load_lds_dwordx4 v130, s[12:13]
	s_add_u32 s12, s8, 0x80000
	v_readfirstlane_b32 s2, v152
	v_add_u32_e32 v153, 0x6000, v147
	s_addc_u32 s13, s9, 0
	s_mov_b32 m0, s2
	v_readfirstlane_b32 s2, v153
	global_load_lds_dwordx4 v174, s[12:13]
	s_mov_b32 m0, s2
	v_ashrrev_i32_e32 v15, 8, v97
	global_load_lds_dwordx4 v130, s[12:13]
	v_mov_b32_e32 v131, v175
	v_lshl_add_u64 v[6:7], s[10:11], 0, v[174:175]
	v_lshl_add_u64 v[4:5], s[10:11], 0, v[130:131]
	v_lshl_add_u64 v[2:3], s[8:9], 0, v[174:175]
	v_lshl_add_u64 v[0:1], s[8:9], 0, v[130:131]
	v_cmp_eq_u32_e32 vcc, 1, v15
	s_and_saveexec_b64 s[12:13], vcc
	s_cbranch_execz .LBB0_183
	s_barrier

.LBB0_476:
	s_waitcnt lgkmcnt(8)
	v_rcp_f32_e32 v81, v78
	s_waitcnt lgkmcnt(7)
	v_rcp_f32_e32 v80, v76
	v_rcp_f32_e32 v79, v77
	s_waitcnt lgkmcnt(6)
	v_rcp_f32_e32 v78, v83
	s_waitcnt lgkmcnt(5)
	v_rcp_f32_e32 v77, v74
	v_rcp_f32_e32 v76, v75
	s_waitcnt lgkmcnt(4)
	v_rcp_f32_e32 v75, v72
	v_rcp_f32_e32 v74, v73
	s_waitcnt lgkmcnt(3)
	v_rcp_f32_e32 v73, v70
	v_rcp_f32_e32 v72, v71
	s_waitcnt lgkmcnt(2)
	v_rcp_f32_e32 v71, v68
	v_rcp_f32_e32 v70, v69
	s_waitcnt lgkmcnt(1)
	v_rcp_f32_e32 v69, v66
	v_rcp_f32_e32 v68, v67
	s_waitcnt lgkmcnt(0)
	v_rcp_f32_e32 v67, v64
	v_rcp_f32_e32 v66, v65
	v_ashrrev_i32_e32 v65, 6, v82
	v_and_b32_e32 v64, 31, v82
	v_bfe_u32 v83, v82, 5, 1
	s_mov_b64 s[6:7], -1
	s_and_b64 vcc, exec, s[10:11]
	s_cbranch_vccnz .LBB0_478
	s_and_b32 s6, s8, 0x70
	s_lshl_b32 s6, s6, 1
	s_lshr_b32 s7, s8, 7
	s_lshl_b32 s7, s7, 4
	s_and_b32 s8, s8, 15
	s_or_b32 s8, s8, s6
	s_or_b32 s8, s8, s7
	s_ashr_i32 s9, s8, 31
	s_lshl_b64 s[6:7], s[8:9], 18
	v_readlane_b32 s8, v254, 36
	s_add_u32 s6, s8, s6
	v_readlane_b32 s8, v255, 0
	s_addc_u32 s7, s8, s7
	s_lshl_b32 s8, s16, 9
	s_add_u32 s6, s6, s8
	s_addc_u32 s7, s7, 0
	s_lshl_b32 s8, s53, 8
	v_lshlrev_b32_e32 v84, 14, v65
	v_lshlrev_b32_e32 v85, 11, v83
	s_add_u32 s6, s6, s8
	v_or3_b32 v84, v85, v84, v64
	s_addc_u32 s7, s7, 0
	v_lshlrev_b32_e32 v84, 1, v84
	v_fma_mixlo_f16 v85, v0, v81, 0
	global_store_short v84, v85, s[6:7]
	v_fma_mixlo_f16 v85, v48, v81, 0
	global_store_short v84, v85, s[6:7] offset:64
	v_fma_mixlo_f16 v85, v32, v81, 0
	global_store_short v84, v85, s[6:7] offset:128
	v_fma_mixlo_f16 v85, v16, v81, 0
	global_store_short v84, v85, s[6:7] offset:192
	v_fma_mixlo_f16 v85, v1, v80, 0
	global_store_short v84, v85, s[6:7] offset:1024
	v_fma_mixlo_f16 v85, v49, v80, 0
	global_store_short v84, v85, s[6:7] offset:1088
	v_fma_mixlo_f16 v85, v33, v80, 0
	global_store_short v84, v85, s[6:7] offset:1152
	v_fma_mixlo_f16 v85, v17, v80, 0
	global_store_short v84, v85, s[6:7] offset:1216
	v_fma_mixlo_f16 v85, v2, v79, 0
	global_store_short v84, v85, s[6:7] offset:2048
	v_fma_mixlo_f16 v85, v50, v79, 0
	global_store_short v84, v85, s[6:7] offset:2112
	v_fma_mixlo_f16 v85, v34, v79, 0
	global_store_short v84, v85, s[6:7] offset:2176
	v_fma_mixlo_f16 v85, v18, v79, 0
	global_store_short v84, v85, s[6:7] offset:2240
	v_fma_mixlo_f16 v85, v3, v78, 0
	global_store_short v84, v85, s[6:7] offset:3072
	v_fma_mixlo_f16 v85, v51, v78, 0
	global_store_short v84, v85, s[6:7] offset:3136
	v_fma_mixlo_f16 v85, v35, v78, 0
	global_store_short v84, v85, s[6:7] offset:3200
	v_fma_mixlo_f16 v85, v19, v78, 0
	global_store_short v84, v85, s[6:7] offset:3264
	v_or_b32_e32 v85, 0x2000, v84
	v_fma_mixlo_f16 v86, v4, v77, 0
	global_store_short v85, v86, s[6:7]
	v_fma_mixlo_f16 v86, v52, v77, 0
	global_store_short v85, v86, s[6:7] offset:64
	v_fma_mixlo_f16 v86, v36, v77, 0
	global_store_short v85, v86, s[6:7] offset:128
	v_fma_mixlo_f16 v86, v20, v77, 0
	global_store_short v85, v86, s[6:7] offset:192
	v_or_b32_e32 v85, 0x2400, v84
	v_fma_mixlo_f16 v86, v5, v76, 0
	global_store_short v85, v86, s[6:7]
	v_fma_mixlo_f16 v86, v53, v76, 0
	global_store_short v85, v86, s[6:7] offset:64
	v_fma_mixlo_f16 v86, v37, v76, 0
	global_store_short v85, v86, s[6:7] offset:128
	v_fma_mixlo_f16 v86, v21, v76, 0
	global_store_short v85, v86, s[6:7] offset:192
	v_or_b32_e32 v85, 0x2800, v84
	v_fma_mixlo_f16 v86, v6, v75, 0
	global_store_short v85, v86, s[6:7]
	v_fma_mixlo_f16 v86, v54, v75, 0
	global_store_short v85, v86, s[6:7] offset:64
	v_fma_mixlo_f16 v86, v38, v75, 0
	global_store_short v85, v86, s[6:7] offset:128
	v_fma_mixlo_f16 v86, v22, v75, 0
	global_store_short v85, v86, s[6:7] offset:192
	v_or_b32_e32 v85, 0x2c00, v84
	v_fma_mixlo_f16 v86, v7, v74, 0
	global_store_short v85, v86, s[6:7]
	v_fma_mixlo_f16 v86, v55, v74, 0
	global_store_short v85, v86, s[6:7] offset:64
	v_fma_mixlo_f16 v86, v39, v74, 0
	global_store_short v85, v86, s[6:7] offset:128
	v_fma_mixlo_f16 v86, v23, v74, 0
	global_store_short v85, v86, s[6:7] offset:192
	v_or_b32_e32 v85, 0x4000, v84
	v_fma_mixlo_f16 v86, v8, v73, 0
	global_store_short v85, v86, s[6:7]
	v_fma_mixlo_f16 v86, v56, v73, 0
	global_store_short v85, v86, s[6:7] offset:64
	v_fma_mixlo_f16 v86, v40, v73, 0
	global_store_short v85, v86, s[6:7] offset:128
	v_fma_mixlo_f16 v86, v24, v73, 0
	global_store_short v85, v86, s[6:7] offset:192
	v_or_b32_e32 v85, 0x4400, v84
	v_fma_mixlo_f16 v86, v9, v72, 0
	global_store_short v85, v86, s[6:7]
	v_fma_mixlo_f16 v86, v57, v72, 0
	global_store_short v85, v86, s[6:7] offset:64
	v_fma_mixlo_f16 v86, v41, v72, 0
	global_store_short v85, v86, s[6:7] offset:128
	v_fma_mixlo_f16 v86, v25, v72, 0
	global_store_short v85, v86, s[6:7] offset:192
	v_or_b32_e32 v85, 0x4800, v84
	v_fma_mixlo_f16 v86, v10, v71, 0
	global_store_short v85, v86, s[6:7]
	v_fma_mixlo_f16 v86, v58, v71, 0
	global_store_short v85, v86, s[6:7] offset:64
	v_fma_mixlo_f16 v86, v42, v71, 0
	global_store_short v85, v86, s[6:7] offset:128
	v_fma_mixlo_f16 v86, v26, v71, 0
	global_store_short v85, v86, s[6:7] offset:192
	v_or_b32_e32 v85, 0x4c00, v84
	v_fma_mixlo_f16 v86, v11, v70, 0
	global_store_short v85, v86, s[6:7]
	v_fma_mixlo_f16 v86, v59, v70, 0
	global_store_short v85, v86, s[6:7] offset:64
	v_fma_mixlo_f16 v86, v43, v70, 0
	global_store_short v85, v86, s[6:7] offset:128
	v_fma_mixlo_f16 v86, v27, v70, 0
	global_store_short v85, v86, s[6:7] offset:192
	v_or_b32_e32 v85, 0x6000, v84
	v_fma_mixlo_f16 v86, v12, v69, 0
	global_store_short v85, v86, s[6:7]
	v_fma_mixlo_f16 v86, v60, v69, 0
	global_store_short v85, v86, s[6:7] offset:64
	v_fma_mixlo_f16 v86, v44, v69, 0
	global_store_short v85, v86, s[6:7] offset:128
	v_fma_mixlo_f16 v86, v28, v69, 0
	global_store_short v85, v86, s[6:7] offset:192
	v_or_b32_e32 v85, 0x6400, v84
	v_fma_mixlo_f16 v86, v13, v68, 0
	global_store_short v85, v86, s[6:7]
	v_fma_mixlo_f16 v86, v61, v68, 0
	global_store_short v85, v86, s[6:7] offset:64
	v_fma_mixlo_f16 v86, v45, v68, 0
	global_store_short v85, v86, s[6:7] offset:128
	v_fma_mixlo_f16 v86, v29, v68, 0
	global_store_short v85, v86, s[6:7] offset:192
	v_or_b32_e32 v85, 0x6800, v84
	v_fma_mixlo_f16 v86, v14, v67, 0
	global_store_short v85, v86, s[6:7]
	v_fma_mixlo_f16 v86, v62, v67, 0
	global_store_short v85, v86, s[6:7] offset:64
	v_fma_mixlo_f16 v86, v46, v67, 0
	global_store_short v85, v86, s[6:7] offset:128
	v_fma_mixlo_f16 v86, v30, v67, 0
	global_store_short v85, v86, s[6:7] offset:192
	v_or_b32_e32 v84, 0x6c00, v84
	v_fma_mixlo_f16 v85, v15, v66, 0
	global_store_short v84, v85, s[6:7]
	v_fma_mixlo_f16 v85, v63, v66, 0
	global_store_short v84, v85, s[6:7] offset:64
	v_fma_mixlo_f16 v85, v47, v66, 0
	global_store_short v84, v85, s[6:7] offset:128
	v_fma_mixlo_f16 v85, v31, v66, 0
	global_store_short v84, v85, s[6:7] offset:192
	s_mov_b64 s[6:7], 0

.LBB0_499:
	s_or_b64 exec, exec, s[6:7]
	v_mov_b32_e32 v0, s10
	s_waitcnt lgkmcnt(0)
	s_barrier
	ds_read_b32 v0, v0
	s_mov_b64 s[6:7], 0x2000
	s_waitcnt lgkmcnt(0)
	v_readfirstlane_b32 s3, v0
	s_cmp_eq_u32 s3, 0
	s_cbranch_scc1 .LBB0_502
	s_lshl_b32 s3, s4, 10
	s_addk_i32 s3, 0x2000
	s_lshl_b32 s4, s4, 8
	s_and_b64 s[0:1], s[0:1], exec
	s_cselect_b32 s4, s4, s3
	s_and_b32 s0, s2, 0x70
	s_lshl_b32 s0, s0, 1
	s_lshr_b32 s1, s2, 7
	s_lshl_b32 s1, s1, 4
	s_and_b32 s2, s2, 15
	s_or_b32 s2, s2, s0
	s_or_b32 s2, s2, s1
	s_ashr_i32 s3, s2, 31
	s_lshl_b64 s[0:1], s[2:3], 18
	v_readlane_b32 s2, v255, 9
	v_readlane_b32 s3, v255, 10
	v_lshlrev_b32_e32 v0, 4, v6
	v_and_b32_e32 v0, 0x3f0, v0
	s_lshl_b32 s5, s12, 8
	v_ashrrev_i32_e32 v5, 1, v6
	s_add_i32 s4, s4, s5
	global_load_dword v4, v175, s[2:3]
	v_readlane_b32 s2, v255, 11
	v_readlane_b32 s3, v255, 12
	v_and_b32_e32 v12, 0xffffffe0, v5
	v_cmp_lt_i32_e32 vcc, v213, v211
	v_add_u32_e32 v14, s4, v12
	v_ashrrev_i32_e32 v15, 31, v14
	v_cndmask_b32_e32 v7, v210, v213, vcc
	global_load_dwordx4 v[0:3], v0, s[2:3]
	s_lshl_b64 s[2:3], s[56:57], 9
	s_add_u32 s2, s92, s2
	s_addc_u32 s3, s93, s3
	v_cmp_lt_i32_e32 vcc, v212, v211
	v_mov_b64_e32 v[10:11], s[2:3]
	v_ashrrev_i32_e32 v13, 31, v12
	s_add_u32 s0, s100, s0
	v_lshlrev_b32_e32 v106, 2, v7
	v_cndmask_b32_e32 v7, v210, v212, vcc
	v_mad_i64_i32 v[10:11], s[4:5], v14, s90, v[10:11]
	v_lshlrev_b64 v[12:13], 10, v[12:13]
	s_addc_u32 s1, s101, s1
	v_lshlrev_b64 v[14:15], 12, v[14:15]
	v_lshlrev_b32_e32 v107, 2, v7
	v_lshl_add_u64 v[12:13], s[0:1], 0, v[12:13]
	v_lshl_add_u64 v[14:15], s[2:3], 0, v[14:15]
	s_mov_b32 s2, -8
	s_waitcnt vmcnt(1)
	v_mov_b32_e32 v5, v4
	s_waitcnt vmcnt(0)
	v_mov_b32_e32 v9, v0
	v_and_b32_e32 v0, 63, v6
	v_mov_b32_e32 v7, v2
	v_lshlrev_b32_e32 v174, 3, v0

.LBB0_506:
	s_waitcnt vmcnt(0)
	v_readlane_b32 s46, v254, 0
	v_readlane_b32 s47, v254, 1
	s_waitcnt vmcnt(63) expcnt(7) lgkmcnt(15)
	s_barrier
	s_and_saveexec_b64 s[0:1], s[46:47]
	v_readlane_b32 s49, v254, 4
	v_readlane_b32 s30, v254, 24
	s_mov_b32 s31, 0xc000
	s_mov_b32 s33, 0xe000
	s_mov_b32 s34, 0xf000
	s_cbranch_execz .LBB0_543
	v_mov_b32_e32 v0, 0x200e8
	ds_read2_b32 v[0:1], v0 offset1:2
	s_waitcnt lgkmcnt(0)
	v_readfirstlane_b32 s2, v0
	s_cmp_eq_u32 s2, 0
	s_cbranch_scc1 .Lslow_C
	v_readlane_b32 s2, v254, 2
	v_readlane_b32 s3, v254, 3
	v_and_b32_e32 v1, 7, v1
	v_lshlrev_b32_e32 v1, 8, v1
	s_add_u32 s2, s2, 0x480
	s_addc_u32 s3, s3, 0
	s_nop 4
	global_atomic_add v0, v1, v209, s[2:3] sc0
	s_waitcnt vmcnt(0)
	v_or_b32_e32 v0, 31, v0
	v_add_u32_e32 v0, 1, v0
	s_mov_b32 s5, 0
	s_nop 0
	v_readfirstlane_b32 s4, v0
	buffer_inv sc1

.LBB0_546:
	v_mov_b32_e32 v97, v208
	s_lshl_b32 s5, s27, 6
	v_ashrrev_i32_e32 v0, 31, v97
	v_lshrrev_b32_e32 v0, 26, v0
	v_add_u32_e32 v0, v97, v0
	v_ashrrev_i32_e32 v8, 6, v0
	v_bfe_i32 v0, v97, 27, 1
	v_lshlrev_b32_e32 v12, 4, v97
	v_lshrrev_b32_e32 v0, 22, v0
	v_add_u32_e32 v0, v12, v0
	v_and_b32_e32 v0, 0xfffffc00, v0
	v_sub_u32_e32 v0, v12, v0
	v_lshrrev_b32_e32 v1, 4, v0
	v_bitop3_b32 v0, v1, v0, 32 bitop3:0x6c
	v_ashrrev_i32_e32 v2, 31, v0
	v_lshrrev_b32_e32 v2, 26, v2
	v_add_u32_e32 v2, v0, v2
	v_ashrrev_i32_e32 v9, 6, v2
	v_and_b32_e32 v2, 0xc0, v2
	v_sub_u32_e32 v0, v0, v2
	v_lshlrev_b32_e32 v1, 3, v8
	v_lshlrev_b32_e32 v3, 5, v8
	v_ashrrev_i16_sdwa v0, v209, sext(v0) dst_sel:DWORD dst_unused:UNUSED_PAD src0_sel:DWORD src1_sel:BYTE_0
	v_and_b32_e32 v1, 0xffff0, v1
	v_and_b32_e32 v3, 32, v3
	v_bfe_i32 v10, v0, 0, 16
	v_add_u32_e32 v0, v3, v10
	v_add_lshl_u32 v1, v9, v1, 12
	s_ashr_i32 s4, s27, 3
	s_and_b32 s5, s5, 0x1c0
	v_lshl_add_u32 v174, v0, 1, v1
	v_add_u32_e32 v0, 0x2000, v12
	s_add_i32 s4, s5, s4
	v_ashrrev_i32_e32 v1, 31, v0
	s_ashr_i32 s5, s4, 31
	v_lshrrev_b32_e32 v1, 22, v1
	s_lshr_b32 s5, s5, 26
	v_add_u32_e32 v1, v0, v1
	s_add_i32 s5, s4, s5
	v_ashrrev_i32_e32 v11, 10, v1
	s_and_b32 s8, s5, 0xffffffc0
	v_mul_i32_i24_e32 v1, 0x400, v11
	s_sub_i32 s4, s4, s8
	v_sub_u32_e32 v0, v0, v1
	s_lshl_b32 s5, s5, 5
	s_lshl_b32 s8, s4, 8
	v_lshrrev_b32_e32 v1, 4, v0
	s_and_b32 s5, s5, 0xfffff800
	s_and_b32 s8, s8, 0x700
	v_bitop3_b32 v0, v1, v0, 32 bitop3:0x6c
	s_or_b32 s8, s8, s5
	s_lshr_b32 s5, s8, 1
	s_and_b32 s5, s5, 0xfffffc00
	s_bfe_u32 s9, s8, 0x1000a
	s_lshl_b32 s9, s9, 13
	s_and_b32 s8, s8, 0x300
	s_or_b32 s8, s8, s5
	s_or_b32 s8, s8, s9
	v_ashrrev_i32_e32 v2, 31, v0
	s_lshl_b32 s4, s4, 5
	v_lshrrev_b32_e32 v2, 26, v2
	s_ashr_i32 s9, s8, 31
	s_and_b32 s4, s4, 0xffffff00
	v_add_u32_e32 v2, v0, v2
	s_lshl_b64 s[10:11], s[8:9], 12
	v_ashrrev_i32_e32 v13, 6, v2
	v_and_b32_e32 v2, 0xc0, v2
	s_add_u32 s10, s18, s10
	v_sub_u32_e32 v0, v0, v2
	s_addc_u32 s11, s19, s11
	s_ashr_i32 s5, s4, 31
	v_lshlrev_b32_e32 v1, 3, v11
	v_lshlrev_b32_e32 v3, 5, v11
	v_ashrrev_i16_sdwa v0, v209, sext(v0) dst_sel:DWORD dst_unused:UNUSED_PAD src0_sel:DWORD src1_sel:BYTE_0
	s_lshl_b64 s[12:13], s[4:5], 12
	v_add_u32_e32 v144, s71, v12
	v_and_b32_e32 v1, 0xffff0, v1
	v_and_b32_e32 v3, 32, v3
	v_bfe_i32 v14, v0, 0, 16
	s_add_u32 s12, s20, s12
	v_readfirstlane_b32 s9, v144
	v_add_u32_e32 v146, 0x2000, v144
	v_add_u32_e32 v0, v3, v14
	v_add_lshl_u32 v1, v13, v1, 12
	s_addc_u32 s13, s21, s13
	s_mov_b32 m0, s9
	v_readfirstlane_b32 s9, v146
	v_add_u32_e32 v147, 0, v12
	v_lshl_add_u32 v130, v0, 1, v1
	global_load_lds_dwordx4 v174, s[12:13]
	s_mov_b32 m0, s9
	v_readfirstlane_b32 s9, v147
	v_add_u32_e32 v148, 0x2000, v147
	global_load_lds_dwordx4 v130, s[12:13]
	s_mov_b32 m0, s9
	v_readfirstlane_b32 s9, v148
	global_load_lds_dwordx4 v174, s[10:11]
	s_mov_b32 m0, s9
	v_readlane_b32 s9, v254, 20
	s_add_u32 s14, s12, 0x80000
	global_load_lds_dwordx4 v130, s[10:11]
	v_add_u32_e32 v149, s9, v12
	v_add_u32_e32 v150, 0x2000, v149
	v_readfirstlane_b32 s9, v149
	s_addc_u32 s15, s13, 0
	s_mov_b32 m0, s9
	v_readfirstlane_b32 s9, v150
	global_load_lds_dwordx4 v174, s[14:15]
	s_mov_b32 m0, s9
	v_add_u32_e32 v152, 0x4000, v147
	global_load_lds_dwordx4 v130, s[14:15]
	s_add_u32 s14, s10, 0x80000
	v_readfirstlane_b32 s9, v152
	v_add_u32_e32 v153, 0x6000, v147
	s_addc_u32 s15, s11, 0
	s_mov_b32 m0, s9
	v_readfirstlane_b32 s9, v153
	global_load_lds_dwordx4 v174, s[14:15]
	s_mov_b32 m0, s9
	v_ashrrev_i32_e32 v15, 8, v97
	global_load_lds_dwordx4 v130, s[14:15]
	v_mov_b32_e32 v131, v175
	v_lshl_add_u64 v[6:7], s[12:13], 0, v[174:175]
	v_lshl_add_u64 v[4:5], s[12:13], 0, v[130:131]
	v_lshl_add_u64 v[2:3], s[10:11], 0, v[174:175]
	v_lshl_add_u64 v[0:1], s[10:11], 0, v[130:131]
	v_cmp_eq_u32_e32 vcc, 1, v15
	s_and_saveexec_b64 s[14:15], vcc
	s_cbranch_execz .LBB0_548
	s_barrier
